# out-proj tile epilogue: second half's residual loads interleaved one-per-row behind the first half's stores (counted vmcnt 15+i / 30-i)
# baseline (speedup 1.0000x reference)
;     ...
;           for (int mf = 0; mf < 4; ++mf)
; #pragma unroll
;             for (int r = 0; r < 4; ++r) {
;               float s = rstdS[(wm * 64 + mf * 16 + 4 * g + r) * NH + h];
; #pragma unroll
;               for (int nf = 0; nf < 4; ++nf) {
;                 accT[mf][nf][r] += s * acc[mf][nf][r];
;                 acc[mf][nf][r] = 0.f;
;               }
;             }
;     ...
;       if (EPI == 1) {
; #pragma unroll
;         for (int r = 0; r < 4; ++r) {
;           const int row = m0 + wm * 64 + mf * 16 + 4 * g + r;
; #pragma unroll
;           for (int nf = 0; nf < 4; ++nf) {
;             const int col = n0 + wn * 64 + nf * 16 + l15;
;             rvv[r][nf] = resid ? resid[(size_t)row * 1024 + col] : xrow(p, row)[col];
;           }
;         }
;       }
; #pragma unroll
;       for (int r = 0; r < 4; ++r) {
;         const int row = m0 + wm * 64 + mf * 16 + 4 * g + r;
;         if (EPI == 0) {
;           u16* proj = (u16*)(p.ws + OFF_PROJ) + (size_t)row * PROJ_LD;
;           if (n0 < 2048) {
;             const float2* rope = (const float2*)(p.ws + OFF_ROPE);
;             const int pi = row < NPROMPT ? (row & 2047) : 2048 + ((row - NPROMPT) & 7);
; #pragma unroll
;             for (int np = 0; np < 2; ++np) {
;               const int pc = n0 + wn * 64 + np * 32;
;               const int i = ((pc & 255) >> 5) * 16 + l15;
;               const float2 cs = rope[pi * 128 + i];
;               const float x1 = acc[mf][2 * np][r], x2 = acc[mf][2 * np + 1][r];
;               float y1 = x1 * cs.x - x2 * cs.y, y2 = x1 * cs.y + x2 * cs.x;
;               if (pc >= 1024) { y1 *= 0.0625f; y2 *= 0.0625f; }
;               const int f1 = (pc & ~255) + i;
;               proj[f1] = f2bf(y1);
;               proj[f1 + 128] = f2bf(y2);
;             }
;           } else {
; #pragma unroll
;             for (int nf = 0; nf < 4; ++nf) proj[n0 + wn * 64 + nf * 16 + l15] = f2bf(acc[mf][nf][r]);
;           }
;         } else if (EPI == 1) {
; #pragma unroll
;           for (int nf = 0; nf < 4; ++nf) {
;             const int col = n0 + wn * 64 + nf * 16 + l15;
;             const float a = (NH > 0) ? accT[mf][nf][r] : acc[mf][nf][r];
;             outf[(size_t)row * 1024 + col] = rvv[r][nf] + a;
;           }
.Lq3_205:
	v_add_u32_e32 v220, 12, v128
	ds_read_b32 v221, v220
	ds_read_b32 v223, v220 offset:256
	ds_read_b32 v225, v220 offset:512
	ds_read_b32 v227, v220 offset:768
	ds_read_b32 v229, v220 offset:2048
	ds_read_b32 v231, v220 offset:2304
	ds_read_b32 v233, v220 offset:2560
	ds_read_b32 v235, v220 offset:2816
	s_waitcnt lgkmcnt(0)
	s_nop 7
	v_mul_f32_e32 v120, v221, v120
	v_mul_f32_e32 v121, v221, v121
	v_mul_f32_e32 v122, v221, v122
	v_mul_f32_e32 v123, v221, v123
	v_mul_f32_e32 v124, v221, v124
	v_mul_f32_e32 v125, v221, v125
	v_mul_f32_e32 v126, v221, v126
	v_mul_f32_e32 v127, v221, v127
	v_mul_f32_e32 v112, v221, v112
	v_mul_f32_e32 v113, v221, v113
	v_mul_f32_e32 v114, v221, v114
	v_mul_f32_e32 v115, v221, v115
	v_mul_f32_e32 v116, v221, v116
	v_mul_f32_e32 v117, v221, v117
	v_mul_f32_e32 v118, v221, v118
	v_mul_f32_e32 v119, v221, v119
	v_mul_f32_e32 v104, v223, v104
	v_mul_f32_e32 v105, v223, v105
	v_mul_f32_e32 v106, v223, v106
	v_mul_f32_e32 v107, v223, v107
	v_mul_f32_e32 v108, v223, v108
	v_mul_f32_e32 v109, v223, v109
	v_mul_f32_e32 v110, v223, v110
	v_mul_f32_e32 v111, v223, v111
	v_mul_f32_e32 v96, v223, v96
	v_mul_f32_e32 v97, v223, v97
	v_mul_f32_e32 v98, v223, v98
	v_mul_f32_e32 v99, v223, v99
	v_mul_f32_e32 v100, v223, v100
	v_mul_f32_e32 v101, v223, v101
	v_mul_f32_e32 v102, v223, v102
	v_mul_f32_e32 v103, v223, v103
	v_mul_f32_e32 v88, v225, v88
	v_mul_f32_e32 v89, v225, v89
	v_mul_f32_e32 v90, v225, v90
	v_mul_f32_e32 v91, v225, v91
	v_mul_f32_e32 v92, v225, v92
	v_mul_f32_e32 v93, v225, v93
	v_mul_f32_e32 v94, v225, v94
	v_mul_f32_e32 v95, v225, v95
	v_mul_f32_e32 v80, v225, v80
	v_mul_f32_e32 v81, v225, v81
	v_mul_f32_e32 v82, v225, v82
	v_mul_f32_e32 v83, v225, v83
	v_mul_f32_e32 v84, v225, v84
	v_mul_f32_e32 v85, v225, v85
	v_mul_f32_e32 v86, v225, v86
	v_mul_f32_e32 v87, v225, v87
	v_mul_f32_e32 v72, v227, v72
	v_mul_f32_e32 v73, v227, v73
	v_mul_f32_e32 v74, v227, v74
	v_mul_f32_e32 v75, v227, v75
	v_mul_f32_e32 v76, v227, v76
	v_mul_f32_e32 v77, v227, v77
	v_mul_f32_e32 v78, v227, v78
	v_mul_f32_e32 v79, v227, v79
	v_mul_f32_e32 v64, v227, v64
	v_mul_f32_e32 v65, v227, v65
	v_mul_f32_e32 v66, v227, v66
	v_mul_f32_e32 v67, v227, v67
	v_mul_f32_e32 v68, v227, v68
	v_mul_f32_e32 v69, v227, v69
	v_mul_f32_e32 v70, v227, v70
	v_mul_f32_e32 v71, v227, v71
	v_mul_f32_e32 v56, v229, v56
	v_mul_f32_e32 v57, v229, v57
	v_mul_f32_e32 v58, v229, v58
	v_mul_f32_e32 v59, v229, v59
	v_mul_f32_e32 v60, v229, v60
	v_mul_f32_e32 v61, v229, v61
	v_mul_f32_e32 v62, v229, v62
	v_mul_f32_e32 v63, v229, v63
	v_mul_f32_e32 v48, v229, v48
	v_mul_f32_e32 v49, v229, v49
	v_mul_f32_e32 v50, v229, v50
	v_mul_f32_e32 v51, v229, v51
	v_mul_f32_e32 v52, v229, v52
	v_mul_f32_e32 v53, v229, v53
	v_mul_f32_e32 v54, v229, v54
	v_mul_f32_e32 v55, v229, v55
	v_mul_f32_e32 v40, v231, v40
	v_mul_f32_e32 v41, v231, v41
	v_mul_f32_e32 v42, v231, v42
	v_mul_f32_e32 v43, v231, v43
	v_mul_f32_e32 v44, v231, v44
	v_mul_f32_e32 v45, v231, v45
	v_mul_f32_e32 v46, v231, v46
	v_mul_f32_e32 v47, v231, v47
	v_mul_f32_e32 v32, v231, v32
	v_mul_f32_e32 v33, v231, v33
	v_mul_f32_e32 v34, v231, v34
	v_mul_f32_e32 v35, v231, v35
	v_mul_f32_e32 v36, v231, v36
	v_mul_f32_e32 v37, v231, v37
	v_mul_f32_e32 v38, v231, v38
	v_mul_f32_e32 v39, v231, v39
	v_mul_f32_e32 v24, v233, v24
	v_mul_f32_e32 v25, v233, v25
	v_mul_f32_e32 v26, v233, v26
	v_mul_f32_e32 v27, v233, v27
	v_mul_f32_e32 v28, v233, v28
	v_mul_f32_e32 v29, v233, v29
	v_mul_f32_e32 v30, v233, v30
	v_mul_f32_e32 v31, v233, v31
	v_mul_f32_e32 v16, v233, v16
	v_mul_f32_e32 v17, v233, v17
	v_mul_f32_e32 v18, v233, v18
	v_mul_f32_e32 v19, v233, v19
	v_mul_f32_e32 v20, v233, v20
	v_mul_f32_e32 v21, v233, v21
	v_mul_f32_e32 v22, v233, v22
	v_mul_f32_e32 v23, v233, v23
	v_mul_f32_e32 v8, v235, v8
	v_mul_f32_e32 v9, v235, v9
	v_mul_f32_e32 v10, v235, v10
	v_mul_f32_e32 v11, v235, v11
	v_mul_f32_e32 v12, v235, v12
	v_mul_f32_e32 v13, v235, v13
	v_mul_f32_e32 v14, v235, v14
	v_mul_f32_e32 v15, v235, v15
	v_mul_f32_e32 v0, v235, v0
	v_mul_f32_e32 v1, v235, v1
	v_mul_f32_e32 v2, v235, v2
	v_mul_f32_e32 v3, v235, v3
	v_mul_f32_e32 v4, v235, v4
	v_mul_f32_e32 v5, v235, v5
	v_mul_f32_e32 v6, v235, v6
	v_mul_f32_e32 v7, v235, v7
	s_barrier
	v_readlane_b32 s4, v255, 51
	v_readlane_b32 s1, v255, 52
	v_readlane_b32 s5, v255, 6
	v_and_b32_e32 v176, 15, v195
	v_lshrrev_b32_e32 v177, 4, v195
	s_lshr_b32 s6, s5, 2
	s_and_b32 s7, s5, 3
	s_lshl_b32 s6, s6, 6
	v_add_u32_e32 v178, s6, v176
	v_mul_u32_u24_e32 v178, 0x410, v178
	s_lshl_b32 s7, s7, 7
	v_lshl_add_u32 v178, v177, 4, v178
	v_add_u32_e32 v178, s7, v178
	s_lshl_b32 s7, s5, 4
	v_lshlrev_b32_e32 v179, 4, v195
	s_mul_i32 s6, s7, 0x410
	v_add_u32_e32 v180, s6, v179
	s_lshl_b32 s4, s4, 8
	s_add_i32 s4, s4, s7
	s_lshl_b32 s4, s4, 12
	s_lshl_b32 s1, s1, 10
	s_add_i32 s4, s4, s1
	v_add_u32_e32 v181, s4, v179
	v_readlane_b32 s0, v255, 0
	v_readlane_b32 s1, v255, 1
	s_load_dwordx2 s[20:21], s[0:1], 0x0
	s_add_u32 s24, s84, 0x15aa2000
	s_addc_u32 s25, s85, 0
	s_waitcnt lgkmcnt(0)
	v_mov_b32_e32 v182, v181
	global_load_dwordx4 v[184:187], v182, s[20:21]
	v_add_u32_e32 v182, 0x1000, v182
	global_load_dwordx4 v[188:191], v182, s[20:21]
	v_add_u32_e32 v182, 0x1000, v182
	global_load_dwordx4 v[196:199], v182, s[20:21]
	v_add_u32_e32 v182, 0x1000, v182
	global_load_dwordx4 v[200:203], v182, s[20:21]
	v_add_u32_e32 v182, 0x1000, v182
	global_load_dwordx4 v[204:207], v182, s[20:21]
	v_add_u32_e32 v182, 0x1000, v182
	global_load_dwordx4 v[208:211], v182, s[20:21]
	v_add_u32_e32 v182, 0x1000, v182
	global_load_dwordx4 v[212:215], v182, s[20:21]
	v_add_u32_e32 v182, 0x1000, v182
	global_load_dwordx4 v[216:219], v182, s[20:21]
	v_add_u32_e32 v182, 0x1000, v182
	global_load_dwordx4 v[220:223], v182, s[20:21]
	v_add_u32_e32 v182, 0x1000, v182
	global_load_dwordx4 v[224:227], v182, s[20:21]
	v_add_u32_e32 v182, 0x1000, v182
	global_load_dwordx4 v[228:231], v182, s[20:21]
	v_add_u32_e32 v182, 0x1000, v182
	global_load_dwordx4 v[232:235], v182, s[20:21]
	v_add_u32_e32 v182, 0x1000, v182
	global_load_dwordx4 v[236:239], v182, s[20:21]
	v_add_u32_e32 v182, 0x1000, v182
	global_load_dwordx4 v[240:243], v182, s[20:21]
	v_add_u32_e32 v182, 0x1000, v182
	global_load_dwordx4 v[244:247], v182, s[20:21]
	v_add_u32_e32 v182, 0x1000, v182
	global_load_dwordx4 v[248:251], v182, s[20:21]
	ds_write_b128 v178, v[120:123]
	ds_write_b128 v178, v[124:127] offset:64
	ds_write_b128 v178, v[104:107] offset:16640
	ds_write_b128 v178, v[108:111] offset:16704
	ds_write_b128 v178, v[88:91] offset:33280
	ds_write_b128 v178, v[92:95] offset:33344
	ds_write_b128 v178, v[72:75] offset:49920
	ds_write_b128 v178, v[76:79] offset:49984
	ds_write_b128 v178, v[112:115] offset:512
	ds_write_b128 v178, v[116:119] offset:576
	ds_write_b128 v178, v[96:99] offset:17152
	ds_write_b128 v178, v[100:103] offset:17216
	ds_write_b128 v178, v[80:83] offset:33792
	ds_write_b128 v178, v[84:87] offset:33856
	ds_write_b128 v178, v[64:67] offset:50432
	ds_write_b128 v178, v[68:71] offset:50496
	s_waitcnt lgkmcnt(0)
	s_barrier
;     ...
;         for (int r = 0; r < 4; ++r) {
;           const int row = m0 + wm * 64 + mf * 16 + 4 * g + r;
; #pragma unroll
;           for (int nf = 0; nf < 4; ++nf) {
;             const int col = n0 + wn * 64 + nf * 16 + l15;
;             rvv[r][nf] = resid ? resid[(size_t)row * 1024 + col] : xrow(p, row)[col];
;           }
;         }
;       }
; #pragma unroll
;       for (int r = 0; r < 4; ++r) {
;         const int row = m0 + wm * 64 + mf * 16 + 4 * g + r;
;         if (EPI == 0) {
;           u16* proj = (u16*)(p.ws + OFF_PROJ) + (size_t)row * PROJ_LD;
;           if (n0 < 2048) {
;             const float2* rope = (const float2*)(p.ws + OFF_ROPE);
;             const int pi = row < NPROMPT ? (row & 2047) : 2048 + ((row - NPROMPT) & 7);
; #pragma unroll
;             for (int np = 0; np < 2; ++np) {
;               const int pc = n0 + wn * 64 + np * 32;
;               const int i = ((pc & 255) >> 5) * 16 + l15;
;               const float2 cs = rope[pi * 128 + i];
;               const float x1 = acc[mf][2 * np][r], x2 = acc[mf][2 * np + 1][r];
;               float y1 = x1 * cs.x - x2 * cs.y, y2 = x1 * cs.y + x2 * cs.x;
;               if (pc >= 1024) { y1 *= 0.0625f; y2 *= 0.0625f; }
;               const int f1 = (pc & ~255) + i;
;               proj[f1] = f2bf(y1);
;               proj[f1 + 128] = f2bf(y2);
;             }
;           } else {
; #pragma unroll
;             for (int nf = 0; nf < 4; ++nf) proj[n0 + wn * 64 + nf * 16 + l15] = f2bf(acc[mf][nf][r]);
;           }
;         } else if (EPI == 1) {
; #pragma unroll
;           for (int nf = 0; nf < 4; ++nf) {
;             const int col = n0 + wn * 64 + nf * 16 + l15;
;             const float a = (NH > 0) ? accT[mf][nf][r] : acc[mf][nf][r];
;             outf[(size_t)row * 1024 + col] = rvv[r][nf] + a;
	ds_read_b128 v[64:67], v180
	ds_read_b128 v[68:71], v180 offset:1040
	ds_read_b128 v[72:75], v180 offset:2080
	ds_read_b128 v[76:79], v180 offset:3120
	ds_read_b128 v[80:83], v180 offset:4160
	ds_read_b128 v[84:87], v180 offset:5200
	ds_read_b128 v[88:91], v180 offset:6240
	ds_read_b128 v[92:95], v180 offset:7280
	ds_read_b128 v[96:99], v180 offset:8320
	ds_read_b128 v[100:103], v180 offset:9360
	ds_read_b128 v[104:107], v180 offset:10400
	ds_read_b128 v[108:111], v180 offset:11440
	ds_read_b128 v[112:115], v180 offset:12480
	ds_read_b128 v[116:119], v180 offset:13520
	ds_read_b128 v[120:123], v180 offset:14560
	ds_read_b128 v[124:127], v180 offset:15600
	s_waitcnt lgkmcnt(0)
	s_barrier
	v_mov_b32_e32 v182, v181
	s_waitcnt vmcnt(15)
	v_add_f32_e32 v64, v64, v184
	v_add_f32_e32 v65, v65, v185
	v_add_f32_e32 v66, v66, v186
	v_add_f32_e32 v67, v67, v187
	global_store_dwordx4 v182, v[64:67], s[24:25]
	v_add_u32_e32 v183, 0x80000, v182
	global_load_dwordx4 v[184:187], v183, s[20:21]
	v_add_u32_e32 v182, 0x1000, v182
	s_waitcnt vmcnt(16)
	v_add_f32_e32 v68, v68, v188
	v_add_f32_e32 v69, v69, v189
	v_add_f32_e32 v70, v70, v190
	v_add_f32_e32 v71, v71, v191
	global_store_dwordx4 v182, v[68:71], s[24:25]
	v_add_u32_e32 v183, 0x80000, v182
	global_load_dwordx4 v[188:191], v183, s[20:21]
	v_add_u32_e32 v182, 0x1000, v182
	s_waitcnt vmcnt(17)
	v_add_f32_e32 v72, v72, v196
	v_add_f32_e32 v73, v73, v197
	v_add_f32_e32 v74, v74, v198
	v_add_f32_e32 v75, v75, v199
	global_store_dwordx4 v182, v[72:75], s[24:25]
	v_add_u32_e32 v183, 0x80000, v182
	global_load_dwordx4 v[196:199], v183, s[20:21]
	v_add_u32_e32 v182, 0x1000, v182
	s_waitcnt vmcnt(18)
	v_add_f32_e32 v76, v76, v200
	v_add_f32_e32 v77, v77, v201
	v_add_f32_e32 v78, v78, v202
	v_add_f32_e32 v79, v79, v203
	global_store_dwordx4 v182, v[76:79], s[24:25]
	v_add_u32_e32 v183, 0x80000, v182
	global_load_dwordx4 v[200:203], v183, s[20:21]
	v_add_u32_e32 v182, 0x1000, v182
	s_waitcnt vmcnt(19)
	v_add_f32_e32 v80, v80, v204
	v_add_f32_e32 v81, v81, v205
	v_add_f32_e32 v82, v82, v206
	v_add_f32_e32 v83, v83, v207
	global_store_dwordx4 v182, v[80:83], s[24:25]
	v_add_u32_e32 v183, 0x80000, v182
	global_load_dwordx4 v[204:207], v183, s[20:21]
	v_add_u32_e32 v182, 0x1000, v182
	s_waitcnt vmcnt(20)
	v_add_f32_e32 v84, v84, v208
	v_add_f32_e32 v85, v85, v209
	v_add_f32_e32 v86, v86, v210
	v_add_f32_e32 v87, v87, v211
	global_store_dwordx4 v182, v[84:87], s[24:25]
	v_add_u32_e32 v183, 0x80000, v182
	global_load_dwordx4 v[208:211], v183, s[20:21]
	v_add_u32_e32 v182, 0x1000, v182
	s_waitcnt vmcnt(21)
	v_add_f32_e32 v88, v88, v212
	v_add_f32_e32 v89, v89, v213
	v_add_f32_e32 v90, v90, v214
	v_add_f32_e32 v91, v91, v215
	global_store_dwordx4 v182, v[88:91], s[24:25]
	v_add_u32_e32 v183, 0x80000, v182
	global_load_dwordx4 v[212:215], v183, s[20:21]
	v_add_u32_e32 v182, 0x1000, v182
	s_waitcnt vmcnt(22)
	v_add_f32_e32 v92, v92, v216
	v_add_f32_e32 v93, v93, v217
	v_add_f32_e32 v94, v94, v218
	v_add_f32_e32 v95, v95, v219
	global_store_dwordx4 v182, v[92:95], s[24:25]
	v_add_u32_e32 v183, 0x80000, v182
	global_load_dwordx4 v[216:219], v183, s[20:21]
	v_add_u32_e32 v182, 0x1000, v182
	s_waitcnt vmcnt(23)
	v_add_f32_e32 v96, v96, v220
	v_add_f32_e32 v97, v97, v221
	v_add_f32_e32 v98, v98, v222
	v_add_f32_e32 v99, v99, v223
	global_store_dwordx4 v182, v[96:99], s[24:25]
	v_add_u32_e32 v183, 0x80000, v182
	global_load_dwordx4 v[220:223], v183, s[20:21]
	v_add_u32_e32 v182, 0x1000, v182
	s_waitcnt vmcnt(24)
	v_add_f32_e32 v100, v100, v224
	v_add_f32_e32 v101, v101, v225
	v_add_f32_e32 v102, v102, v226
	v_add_f32_e32 v103, v103, v227
	global_store_dwordx4 v182, v[100:103], s[24:25]
	v_add_u32_e32 v183, 0x80000, v182
	global_load_dwordx4 v[224:227], v183, s[20:21]
	v_add_u32_e32 v182, 0x1000, v182
	s_waitcnt vmcnt(25)
	v_add_f32_e32 v104, v104, v228
	v_add_f32_e32 v105, v105, v229
	v_add_f32_e32 v106, v106, v230
	v_add_f32_e32 v107, v107, v231
	global_store_dwordx4 v182, v[104:107], s[24:25]
	v_add_u32_e32 v183, 0x80000, v182
	global_load_dwordx4 v[228:231], v183, s[20:21]
	v_add_u32_e32 v182, 0x1000, v182
	s_waitcnt vmcnt(26)
	v_add_f32_e32 v108, v108, v232
	v_add_f32_e32 v109, v109, v233
	v_add_f32_e32 v110, v110, v234
	v_add_f32_e32 v111, v111, v235
	global_store_dwordx4 v182, v[108:111], s[24:25]
	v_add_u32_e32 v183, 0x80000, v182
	global_load_dwordx4 v[232:235], v183, s[20:21]
	v_add_u32_e32 v182, 0x1000, v182
	s_waitcnt vmcnt(27)
	v_add_f32_e32 v112, v112, v236
	v_add_f32_e32 v113, v113, v237
	v_add_f32_e32 v114, v114, v238
	v_add_f32_e32 v115, v115, v239
	global_store_dwordx4 v182, v[112:115], s[24:25]
	v_add_u32_e32 v183, 0x80000, v182
	global_load_dwordx4 v[236:239], v183, s[20:21]
	v_add_u32_e32 v182, 0x1000, v182
	s_waitcnt vmcnt(28)
	v_add_f32_e32 v116, v116, v240
	v_add_f32_e32 v117, v117, v241
	v_add_f32_e32 v118, v118, v242
	v_add_f32_e32 v119, v119, v243
	global_store_dwordx4 v182, v[116:119], s[24:25]
	v_add_u32_e32 v183, 0x80000, v182
	global_load_dwordx4 v[240:243], v183, s[20:21]
	v_add_u32_e32 v182, 0x1000, v182
	s_waitcnt vmcnt(29)
	v_add_f32_e32 v120, v120, v244
	v_add_f32_e32 v121, v121, v245
	v_add_f32_e32 v122, v122, v246
	v_add_f32_e32 v123, v123, v247
	global_store_dwordx4 v182, v[120:123], s[24:25]
	v_add_u32_e32 v183, 0x80000, v182
	global_load_dwordx4 v[244:247], v183, s[20:21]
	v_add_u32_e32 v182, 0x1000, v182
	s_waitcnt vmcnt(30)
	v_add_f32_e32 v124, v124, v248
	v_add_f32_e32 v125, v125, v249
	v_add_f32_e32 v126, v126, v250
	v_add_f32_e32 v127, v127, v251
	global_store_dwordx4 v182, v[124:127], s[24:25]
	v_add_u32_e32 v183, 0x80000, v182
	global_load_dwordx4 v[248:251], v183, s[20:21]
	v_add_u32_e32 v181, 0x80000, v181
	ds_write_b128 v178, v[56:59]
	ds_write_b128 v178, v[60:63] offset:64
	ds_write_b128 v178, v[40:43] offset:16640
	ds_write_b128 v178, v[44:47] offset:16704
	ds_write_b128 v178, v[24:27] offset:33280
	ds_write_b128 v178, v[28:31] offset:33344
	ds_write_b128 v178, v[8:11] offset:49920
	ds_write_b128 v178, v[12:15] offset:49984
	ds_write_b128 v178, v[48:51] offset:512
	ds_write_b128 v178, v[52:55] offset:576
	ds_write_b128 v178, v[32:35] offset:17152
	ds_write_b128 v178, v[36:39] offset:17216
	ds_write_b128 v178, v[16:19] offset:33792
	ds_write_b128 v178, v[20:23] offset:33856
	ds_write_b128 v178, v[0:3] offset:50432
	ds_write_b128 v178, v[4:7] offset:50496
	s_waitcnt lgkmcnt(0)
	s_barrier
;     ...
;         for (int r = 0; r < 4; ++r) {
;           const int row = m0 + wm * 64 + mf * 16 + 4 * g + r;
; #pragma unroll
;           for (int nf = 0; nf < 4; ++nf) {
;             const int col = n0 + wn * 64 + nf * 16 + l15;
;             rvv[r][nf] = resid ? resid[(size_t)row * 1024 + col] : xrow(p, row)[col];
;           }
;         }
;       }
; #pragma unroll
;       for (int r = 0; r < 4; ++r) {
;         const int row = m0 + wm * 64 + mf * 16 + 4 * g + r;
;         if (EPI == 0) {
;           u16* proj = (u16*)(p.ws + OFF_PROJ) + (size_t)row * PROJ_LD;
;           if (n0 < 2048) {
;             const float2* rope = (const float2*)(p.ws + OFF_ROPE);
;             const int pi = row < NPROMPT ? (row & 2047) : 2048 + ((row - NPROMPT) & 7);
; #pragma unroll
;             for (int np = 0; np < 2; ++np) {
;               const int pc = n0 + wn * 64 + np * 32;
;               const int i = ((pc & 255) >> 5) * 16 + l15;
;               const float2 cs = rope[pi * 128 + i];
;               const float x1 = acc[mf][2 * np][r], x2 = acc[mf][2 * np + 1][r];
;               float y1 = x1 * cs.x - x2 * cs.y, y2 = x1 * cs.y + x2 * cs.x;
;               if (pc >= 1024) { y1 *= 0.0625f; y2 *= 0.0625f; }
;               const int f1 = (pc & ~255) + i;
;               proj[f1] = f2bf(y1);
;               proj[f1 + 128] = f2bf(y2);
;             }
;           } else {
; #pragma unroll
;             for (int nf = 0; nf < 4; ++nf) proj[n0 + wn * 64 + nf * 16 + l15] = f2bf(acc[mf][nf][r]);
;           }
;         } else if (EPI == 1) {
; #pragma unroll
;           for (int nf = 0; nf < 4; ++nf) {
;             const int col = n0 + wn * 64 + nf * 16 + l15;
;             const float a = (NH > 0) ? accT[mf][nf][r] : acc[mf][nf][r];
;             outf[(size_t)row * 1024 + col] = rvv[r][nf] + a;
	ds_read_b128 v[64:67], v180
	ds_read_b128 v[68:71], v180 offset:1040
	ds_read_b128 v[72:75], v180 offset:2080
	ds_read_b128 v[76:79], v180 offset:3120
	ds_read_b128 v[80:83], v180 offset:4160
	ds_read_b128 v[84:87], v180 offset:5200
	ds_read_b128 v[88:91], v180 offset:6240
	ds_read_b128 v[92:95], v180 offset:7280
	ds_read_b128 v[96:99], v180 offset:8320
	ds_read_b128 v[100:103], v180 offset:9360
	ds_read_b128 v[104:107], v180 offset:10400
	ds_read_b128 v[108:111], v180 offset:11440
	ds_read_b128 v[112:115], v180 offset:12480
	ds_read_b128 v[116:119], v180 offset:13520
	ds_read_b128 v[120:123], v180 offset:14560
	ds_read_b128 v[124:127], v180 offset:15600
	s_waitcnt lgkmcnt(0)
	s_barrier
	v_mov_b32_e32 v182, v181
	s_waitcnt vmcnt(30)
	v_add_f32_e32 v64, v64, v184
	v_add_f32_e32 v65, v65, v185
	v_add_f32_e32 v66, v66, v186
	v_add_f32_e32 v67, v67, v187
	global_store_dwordx4 v182, v[64:67], s[24:25]
	v_add_u32_e32 v182, 0x1000, v182
	s_waitcnt vmcnt(29)
	v_add_f32_e32 v68, v68, v188
	v_add_f32_e32 v69, v69, v189
	v_add_f32_e32 v70, v70, v190
	v_add_f32_e32 v71, v71, v191
	global_store_dwordx4 v182, v[68:71], s[24:25]
	v_add_u32_e32 v182, 0x1000, v182
	s_waitcnt vmcnt(28)
	v_add_f32_e32 v72, v72, v196
	v_add_f32_e32 v73, v73, v197
	v_add_f32_e32 v74, v74, v198
	v_add_f32_e32 v75, v75, v199
	global_store_dwordx4 v182, v[72:75], s[24:25]
	v_add_u32_e32 v182, 0x1000, v182
	s_waitcnt vmcnt(27)
	v_add_f32_e32 v76, v76, v200
	v_add_f32_e32 v77, v77, v201
	v_add_f32_e32 v78, v78, v202
	v_add_f32_e32 v79, v79, v203
	global_store_dwordx4 v182, v[76:79], s[24:25]
	v_add_u32_e32 v182, 0x1000, v182
	s_waitcnt vmcnt(26)
	v_add_f32_e32 v80, v80, v204
	v_add_f32_e32 v81, v81, v205
	v_add_f32_e32 v82, v82, v206
	v_add_f32_e32 v83, v83, v207
	global_store_dwordx4 v182, v[80:83], s[24:25]
	v_add_u32_e32 v182, 0x1000, v182
	s_waitcnt vmcnt(25)
	v_add_f32_e32 v84, v84, v208
	v_add_f32_e32 v85, v85, v209
	v_add_f32_e32 v86, v86, v210
	v_add_f32_e32 v87, v87, v211
	global_store_dwordx4 v182, v[84:87], s[24:25]
	v_add_u32_e32 v182, 0x1000, v182
	s_waitcnt vmcnt(24)
	v_add_f32_e32 v88, v88, v212
	v_add_f32_e32 v89, v89, v213
	v_add_f32_e32 v90, v90, v214
	v_add_f32_e32 v91, v91, v215
	global_store_dwordx4 v182, v[88:91], s[24:25]
	v_add_u32_e32 v182, 0x1000, v182
	s_waitcnt vmcnt(23)
	v_add_f32_e32 v92, v92, v216
	v_add_f32_e32 v93, v93, v217
	v_add_f32_e32 v94, v94, v218
	v_add_f32_e32 v95, v95, v219
	global_store_dwordx4 v182, v[92:95], s[24:25]
	v_add_u32_e32 v182, 0x1000, v182
	s_waitcnt vmcnt(22)
	v_add_f32_e32 v96, v96, v220
	v_add_f32_e32 v97, v97, v221
	v_add_f32_e32 v98, v98, v222
	v_add_f32_e32 v99, v99, v223
	global_store_dwordx4 v182, v[96:99], s[24:25]
	v_add_u32_e32 v182, 0x1000, v182
	s_waitcnt vmcnt(21)
	v_add_f32_e32 v100, v100, v224
	v_add_f32_e32 v101, v101, v225
	v_add_f32_e32 v102, v102, v226
	v_add_f32_e32 v103, v103, v227
	global_store_dwordx4 v182, v[100:103], s[24:25]
	v_add_u32_e32 v182, 0x1000, v182
	s_waitcnt vmcnt(20)
	v_add_f32_e32 v104, v104, v228
	v_add_f32_e32 v105, v105, v229
	v_add_f32_e32 v106, v106, v230
	v_add_f32_e32 v107, v107, v231
	global_store_dwordx4 v182, v[104:107], s[24:25]
	v_add_u32_e32 v182, 0x1000, v182
	s_waitcnt vmcnt(19)
	v_add_f32_e32 v108, v108, v232
	v_add_f32_e32 v109, v109, v233
	v_add_f32_e32 v110, v110, v234
	v_add_f32_e32 v111, v111, v235
	global_store_dwordx4 v182, v[108:111], s[24:25]
	v_add_u32_e32 v182, 0x1000, v182
	s_waitcnt vmcnt(18)
	v_add_f32_e32 v112, v112, v236
	v_add_f32_e32 v113, v113, v237
	v_add_f32_e32 v114, v114, v238
	v_add_f32_e32 v115, v115, v239
	global_store_dwordx4 v182, v[112:115], s[24:25]
	v_add_u32_e32 v182, 0x1000, v182
	s_waitcnt vmcnt(17)
	v_add_f32_e32 v116, v116, v240
	v_add_f32_e32 v117, v117, v241
	v_add_f32_e32 v118, v118, v242
	v_add_f32_e32 v119, v119, v243
	global_store_dwordx4 v182, v[116:119], s[24:25]
	v_add_u32_e32 v182, 0x1000, v182
	s_waitcnt vmcnt(16)
	v_add_f32_e32 v120, v120, v244
	v_add_f32_e32 v121, v121, v245
	v_add_f32_e32 v122, v122, v246
	v_add_f32_e32 v123, v123, v247
	global_store_dwordx4 v182, v[120:123], s[24:25]
	v_add_u32_e32 v182, 0x1000, v182
	s_waitcnt vmcnt(15)
	v_add_f32_e32 v124, v124, v248
	v_add_f32_e32 v125, v125, v249
	v_add_f32_e32 v126, v126, v250
	v_add_f32_e32 v127, v127, v251
	global_store_dwordx4 v182, v[124:127], s[24:25]
	s_waitcnt vmcnt(0)
	s_barrier
	s_add_i32 s70, s70, s96
	s_cmp_lt_u32 s70, 0x100
	s_cbranch_scc1 .Lq3_tile

;     ...
;           for (int mf = 0; mf < 4; ++mf)
; #pragma unroll
;             for (int r = 0; r < 4; ++r) {
;               float s = rstdS[(wm * 64 + mf * 16 + 4 * g + r) * NH + h];
; #pragma unroll
;               for (int nf = 0; nf < 4; ++nf) {
;                 accT[mf][nf][r] += s * acc[mf][nf][r];
;                 acc[mf][nf][r] = 0.f;
;               }
;             }
;     ...
;       if (EPI == 1) {
; #pragma unroll
;         for (int r = 0; r < 4; ++r) {
;           const int row = m0 + wm * 64 + mf * 16 + 4 * g + r;
; #pragma unroll
;           for (int nf = 0; nf < 4; ++nf) {
;             const int col = n0 + wn * 64 + nf * 16 + l15;
;             rvv[r][nf] = resid ? resid[(size_t)row * 1024 + col] : xrow(p, row)[col];
;           }
;         }
;       }
; #pragma unroll
;       for (int r = 0; r < 4; ++r) {
;         const int row = m0 + wm * 64 + mf * 16 + 4 * g + r;
;         if (EPI == 0) {
;           u16* proj = (u16*)(p.ws + OFF_PROJ) + (size_t)row * PROJ_LD;
;           if (n0 < 2048) {
;             const float2* rope = (const float2*)(p.ws + OFF_ROPE);
;             const int pi = row < NPROMPT ? (row & 2047) : 2048 + ((row - NPROMPT) & 7);
; #pragma unroll
;             for (int np = 0; np < 2; ++np) {
;               const int pc = n0 + wn * 64 + np * 32;
;               const int i = ((pc & 255) >> 5) * 16 + l15;
;               const float2 cs = rope[pi * 128 + i];
;               const float x1 = acc[mf][2 * np][r], x2 = acc[mf][2 * np + 1][r];
;               float y1 = x1 * cs.x - x2 * cs.y, y2 = x1 * cs.y + x2 * cs.x;
;               if (pc >= 1024) { y1 *= 0.0625f; y2 *= 0.0625f; }
;               const int f1 = (pc & ~255) + i;
;               proj[f1] = f2bf(y1);
;               proj[f1 + 128] = f2bf(y2);
;             }
;           } else {
; #pragma unroll
;             for (int nf = 0; nf < 4; ++nf) proj[n0 + wn * 64 + nf * 16 + l15] = f2bf(acc[mf][nf][r]);
;           }
;         } else if (EPI == 1) {
; #pragma unroll
;           for (int nf = 0; nf < 4; ++nf) {
;             const int col = n0 + wn * 64 + nf * 16 + l15;
;             const float a = (NH > 0) ? accT[mf][nf][r] : acc[mf][nf][r];
;             outf[(size_t)row * 1024 + col] = rvv[r][nf] + a;
;           }
.Lq8_205:
	v_add_u32_e32 v220, 28, v128
	ds_read_b32 v221, v220
	ds_read_b32 v223, v220 offset:512
	ds_read_b32 v225, v220 offset:1024
	ds_read_b32 v227, v220 offset:1536
	ds_read_b32 v229, v220 offset:4096
	ds_read_b32 v231, v220 offset:4608
	ds_read_b32 v233, v220 offset:5120
	ds_read_b32 v235, v220 offset:5632
	s_waitcnt lgkmcnt(0)
	s_nop 7
	v_mul_f32_e32 v120, v221, v120
	v_mul_f32_e32 v121, v221, v121
	v_mul_f32_e32 v122, v221, v122
	v_mul_f32_e32 v123, v221, v123
	v_mul_f32_e32 v124, v221, v124
	v_mul_f32_e32 v125, v221, v125
	v_mul_f32_e32 v126, v221, v126
	v_mul_f32_e32 v127, v221, v127
	v_mul_f32_e32 v112, v221, v112
	v_mul_f32_e32 v113, v221, v113
	v_mul_f32_e32 v114, v221, v114
	v_mul_f32_e32 v115, v221, v115
	v_mul_f32_e32 v116, v221, v116
	v_mul_f32_e32 v117, v221, v117
	v_mul_f32_e32 v118, v221, v118
	v_mul_f32_e32 v119, v221, v119
	v_mul_f32_e32 v104, v223, v104
	v_mul_f32_e32 v105, v223, v105
	v_mul_f32_e32 v106, v223, v106
	v_mul_f32_e32 v107, v223, v107
	v_mul_f32_e32 v108, v223, v108
	v_mul_f32_e32 v109, v223, v109
	v_mul_f32_e32 v110, v223, v110
	v_mul_f32_e32 v111, v223, v111
	v_mul_f32_e32 v96, v223, v96
	v_mul_f32_e32 v97, v223, v97
	v_mul_f32_e32 v98, v223, v98
	v_mul_f32_e32 v99, v223, v99
	v_mul_f32_e32 v100, v223, v100
	v_mul_f32_e32 v101, v223, v101
	v_mul_f32_e32 v102, v223, v102
	v_mul_f32_e32 v103, v223, v103
	v_mul_f32_e32 v88, v225, v88
	v_mul_f32_e32 v89, v225, v89
	v_mul_f32_e32 v90, v225, v90
	v_mul_f32_e32 v91, v225, v91
	v_mul_f32_e32 v92, v225, v92
	v_mul_f32_e32 v93, v225, v93
	v_mul_f32_e32 v94, v225, v94
	v_mul_f32_e32 v95, v225, v95
	v_mul_f32_e32 v80, v225, v80
	v_mul_f32_e32 v81, v225, v81
	v_mul_f32_e32 v82, v225, v82
	v_mul_f32_e32 v83, v225, v83
	v_mul_f32_e32 v84, v225, v84
	v_mul_f32_e32 v85, v225, v85
	v_mul_f32_e32 v86, v225, v86
	v_mul_f32_e32 v87, v225, v87
	v_mul_f32_e32 v72, v227, v72
	v_mul_f32_e32 v73, v227, v73
	v_mul_f32_e32 v74, v227, v74
	v_mul_f32_e32 v75, v227, v75
	v_mul_f32_e32 v76, v227, v76
	v_mul_f32_e32 v77, v227, v77
	v_mul_f32_e32 v78, v227, v78
	v_mul_f32_e32 v79, v227, v79
	v_mul_f32_e32 v64, v227, v64
	v_mul_f32_e32 v65, v227, v65
	v_mul_f32_e32 v66, v227, v66
	v_mul_f32_e32 v67, v227, v67
	v_mul_f32_e32 v68, v227, v68
	v_mul_f32_e32 v69, v227, v69
	v_mul_f32_e32 v70, v227, v70
	v_mul_f32_e32 v71, v227, v71
	v_mul_f32_e32 v56, v229, v56
	v_mul_f32_e32 v57, v229, v57
	v_mul_f32_e32 v58, v229, v58
	v_mul_f32_e32 v59, v229, v59
	v_mul_f32_e32 v60, v229, v60
	v_mul_f32_e32 v61, v229, v61
	v_mul_f32_e32 v62, v229, v62
	v_mul_f32_e32 v63, v229, v63
	v_mul_f32_e32 v48, v229, v48
	v_mul_f32_e32 v49, v229, v49
	v_mul_f32_e32 v50, v229, v50
	v_mul_f32_e32 v51, v229, v51
	v_mul_f32_e32 v52, v229, v52
	v_mul_f32_e32 v53, v229, v53
	v_mul_f32_e32 v54, v229, v54
	v_mul_f32_e32 v55, v229, v55
	v_mul_f32_e32 v40, v231, v40
	v_mul_f32_e32 v41, v231, v41
	v_mul_f32_e32 v42, v231, v42
	v_mul_f32_e32 v43, v231, v43
	v_mul_f32_e32 v44, v231, v44
	v_mul_f32_e32 v45, v231, v45
	v_mul_f32_e32 v46, v231, v46
	v_mul_f32_e32 v47, v231, v47
	v_mul_f32_e32 v32, v231, v32
	v_mul_f32_e32 v33, v231, v33
	v_mul_f32_e32 v34, v231, v34
	v_mul_f32_e32 v35, v231, v35
	v_mul_f32_e32 v36, v231, v36
	v_mul_f32_e32 v37, v231, v37
	v_mul_f32_e32 v38, v231, v38
	v_mul_f32_e32 v39, v231, v39
	v_mul_f32_e32 v24, v233, v24
	v_mul_f32_e32 v25, v233, v25
	v_mul_f32_e32 v26, v233, v26
	v_mul_f32_e32 v27, v233, v27
	v_mul_f32_e32 v28, v233, v28
	v_mul_f32_e32 v29, v233, v29
	v_mul_f32_e32 v30, v233, v30
	v_mul_f32_e32 v31, v233, v31
	v_mul_f32_e32 v16, v233, v16
	v_mul_f32_e32 v17, v233, v17
	v_mul_f32_e32 v18, v233, v18
	v_mul_f32_e32 v19, v233, v19
	v_mul_f32_e32 v20, v233, v20
	v_mul_f32_e32 v21, v233, v21
	v_mul_f32_e32 v22, v233, v22
	v_mul_f32_e32 v23, v233, v23
	v_mul_f32_e32 v8, v235, v8
	v_mul_f32_e32 v9, v235, v9
	v_mul_f32_e32 v10, v235, v10
	v_mul_f32_e32 v11, v235, v11
	v_mul_f32_e32 v12, v235, v12
	v_mul_f32_e32 v13, v235, v13
	v_mul_f32_e32 v14, v235, v14
	v_mul_f32_e32 v15, v235, v15
	v_mul_f32_e32 v0, v235, v0
	v_mul_f32_e32 v1, v235, v1
	v_mul_f32_e32 v2, v235, v2
	v_mul_f32_e32 v3, v235, v3
	v_mul_f32_e32 v4, v235, v4
	v_mul_f32_e32 v5, v235, v5
	v_mul_f32_e32 v6, v235, v6
	v_mul_f32_e32 v7, v235, v7
	s_barrier
	v_readlane_b32 s4, v255, 51
	v_readlane_b32 s1, v255, 52
	v_readlane_b32 s5, v255, 6
	v_and_b32_e32 v176, 15, v195
	v_lshrrev_b32_e32 v177, 4, v195
	s_lshr_b32 s6, s5, 2
	s_and_b32 s7, s5, 3
	s_lshl_b32 s6, s6, 6
	v_add_u32_e32 v178, s6, v176
	v_mul_u32_u24_e32 v178, 0x410, v178
	s_lshl_b32 s7, s7, 7
	v_lshl_add_u32 v178, v177, 4, v178
	v_add_u32_e32 v178, s7, v178
	s_lshl_b32 s7, s5, 4
	v_lshlrev_b32_e32 v179, 4, v195
	s_mul_i32 s6, s7, 0x410
	v_add_u32_e32 v180, s6, v179
	s_lshl_b32 s4, s4, 8
	s_add_i32 s4, s4, s7
	s_lshl_b32 s4, s4, 12
	s_lshl_b32 s1, s1, 10
	s_add_i32 s4, s4, s1
	v_add_u32_e32 v181, s4, v179
	s_add_u32 s20, s84, 0x15aa2000
	s_addc_u32 s21, s85, 0
	s_add_u32 s24, s84, 0x19ea2000
	s_addc_u32 s25, s85, 0
	v_mov_b32_e32 v182, v181
	global_load_dwordx4 v[184:187], v182, s[20:21]
	v_add_u32_e32 v182, 0x1000, v182
	global_load_dwordx4 v[188:191], v182, s[20:21]
	v_add_u32_e32 v182, 0x1000, v182
	global_load_dwordx4 v[196:199], v182, s[20:21]
	v_add_u32_e32 v182, 0x1000, v182
	global_load_dwordx4 v[200:203], v182, s[20:21]
	v_add_u32_e32 v182, 0x1000, v182
	global_load_dwordx4 v[204:207], v182, s[20:21]
	v_add_u32_e32 v182, 0x1000, v182
	global_load_dwordx4 v[208:211], v182, s[20:21]
	v_add_u32_e32 v182, 0x1000, v182
	global_load_dwordx4 v[212:215], v182, s[20:21]
	v_add_u32_e32 v182, 0x1000, v182
	global_load_dwordx4 v[216:219], v182, s[20:21]
	v_add_u32_e32 v182, 0x1000, v182
	global_load_dwordx4 v[220:223], v182, s[20:21]
	v_add_u32_e32 v182, 0x1000, v182
	global_load_dwordx4 v[224:227], v182, s[20:21]
	v_add_u32_e32 v182, 0x1000, v182
	global_load_dwordx4 v[228:231], v182, s[20:21]
	v_add_u32_e32 v182, 0x1000, v182
	global_load_dwordx4 v[232:235], v182, s[20:21]
	v_add_u32_e32 v182, 0x1000, v182
	global_load_dwordx4 v[236:239], v182, s[20:21]
	v_add_u32_e32 v182, 0x1000, v182
	global_load_dwordx4 v[240:243], v182, s[20:21]
	v_add_u32_e32 v182, 0x1000, v182
	global_load_dwordx4 v[244:247], v182, s[20:21]
	v_add_u32_e32 v182, 0x1000, v182
	global_load_dwordx4 v[248:251], v182, s[20:21]
	ds_write_b128 v178, v[120:123]
	ds_write_b128 v178, v[124:127] offset:64
	ds_write_b128 v178, v[104:107] offset:16640
	ds_write_b128 v178, v[108:111] offset:16704
	ds_write_b128 v178, v[88:91] offset:33280
	ds_write_b128 v178, v[92:95] offset:33344
	ds_write_b128 v178, v[72:75] offset:49920
	ds_write_b128 v178, v[76:79] offset:49984
	ds_write_b128 v178, v[112:115] offset:512
	ds_write_b128 v178, v[116:119] offset:576
	ds_write_b128 v178, v[96:99] offset:17152
	ds_write_b128 v178, v[100:103] offset:17216
	ds_write_b128 v178, v[80:83] offset:33792
	ds_write_b128 v178, v[84:87] offset:33856
	ds_write_b128 v178, v[64:67] offset:50432
	ds_write_b128 v178, v[68:71] offset:50496
	s_waitcnt lgkmcnt(0)
	s_barrier
;     ...
;         for (int r = 0; r < 4; ++r) {
;           const int row = m0 + wm * 64 + mf * 16 + 4 * g + r;
; #pragma unroll
;           for (int nf = 0; nf < 4; ++nf) {
;             const int col = n0 + wn * 64 + nf * 16 + l15;
;             rvv[r][nf] = resid ? resid[(size_t)row * 1024 + col] : xrow(p, row)[col];
;           }
;         }
;       }
; #pragma unroll
;       for (int r = 0; r < 4; ++r) {
;         const int row = m0 + wm * 64 + mf * 16 + 4 * g + r;
;         if (EPI == 0) {
;           u16* proj = (u16*)(p.ws + OFF_PROJ) + (size_t)row * PROJ_LD;
;           if (n0 < 2048) {
;             const float2* rope = (const float2*)(p.ws + OFF_ROPE);
;             const int pi = row < NPROMPT ? (row & 2047) : 2048 + ((row - NPROMPT) & 7);
; #pragma unroll
;             for (int np = 0; np < 2; ++np) {
;               const int pc = n0 + wn * 64 + np * 32;
;               const int i = ((pc & 255) >> 5) * 16 + l15;
;               const float2 cs = rope[pi * 128 + i];
;               const float x1 = acc[mf][2 * np][r], x2 = acc[mf][2 * np + 1][r];
;               float y1 = x1 * cs.x - x2 * cs.y, y2 = x1 * cs.y + x2 * cs.x;
;               if (pc >= 1024) { y1 *= 0.0625f; y2 *= 0.0625f; }
;               const int f1 = (pc & ~255) + i;
;               proj[f1] = f2bf(y1);
;               proj[f1 + 128] = f2bf(y2);
;             }
;           } else {
; #pragma unroll
;             for (int nf = 0; nf < 4; ++nf) proj[n0 + wn * 64 + nf * 16 + l15] = f2bf(acc[mf][nf][r]);
;           }
;         } else if (EPI == 1) {
; #pragma unroll
;           for (int nf = 0; nf < 4; ++nf) {
;             const int col = n0 + wn * 64 + nf * 16 + l15;
;             const float a = (NH > 0) ? accT[mf][nf][r] : acc[mf][nf][r];
;             outf[(size_t)row * 1024 + col] = rvv[r][nf] + a;
	ds_read_b128 v[64:67], v180
	ds_read_b128 v[68:71], v180 offset:1040
	ds_read_b128 v[72:75], v180 offset:2080
	ds_read_b128 v[76:79], v180 offset:3120
	ds_read_b128 v[80:83], v180 offset:4160
	ds_read_b128 v[84:87], v180 offset:5200
	ds_read_b128 v[88:91], v180 offset:6240
	ds_read_b128 v[92:95], v180 offset:7280
	ds_read_b128 v[96:99], v180 offset:8320
	ds_read_b128 v[100:103], v180 offset:9360
	ds_read_b128 v[104:107], v180 offset:10400
	ds_read_b128 v[108:111], v180 offset:11440
	ds_read_b128 v[112:115], v180 offset:12480
	ds_read_b128 v[116:119], v180 offset:13520
	ds_read_b128 v[120:123], v180 offset:14560
	ds_read_b128 v[124:127], v180 offset:15600
	s_waitcnt lgkmcnt(0)
	s_barrier
	v_mov_b32_e32 v182, v181
	s_waitcnt vmcnt(15)
	v_add_f32_e32 v64, v64, v184
	v_add_f32_e32 v65, v65, v185
	v_add_f32_e32 v66, v66, v186
	v_add_f32_e32 v67, v67, v187
	global_store_dwordx4 v182, v[64:67], s[24:25]
	v_add_u32_e32 v183, 0x80000, v182
	global_load_dwordx4 v[184:187], v183, s[20:21]
	v_add_u32_e32 v182, 0x1000, v182
	s_waitcnt vmcnt(16)
	v_add_f32_e32 v68, v68, v188
	v_add_f32_e32 v69, v69, v189
	v_add_f32_e32 v70, v70, v190
	v_add_f32_e32 v71, v71, v191
	global_store_dwordx4 v182, v[68:71], s[24:25]
	v_add_u32_e32 v183, 0x80000, v182
	global_load_dwordx4 v[188:191], v183, s[20:21]
	v_add_u32_e32 v182, 0x1000, v182
	s_waitcnt vmcnt(17)
	v_add_f32_e32 v72, v72, v196
	v_add_f32_e32 v73, v73, v197
	v_add_f32_e32 v74, v74, v198
	v_add_f32_e32 v75, v75, v199
	global_store_dwordx4 v182, v[72:75], s[24:25]
	v_add_u32_e32 v183, 0x80000, v182
	global_load_dwordx4 v[196:199], v183, s[20:21]
	v_add_u32_e32 v182, 0x1000, v182
	s_waitcnt vmcnt(18)
	v_add_f32_e32 v76, v76, v200
	v_add_f32_e32 v77, v77, v201
	v_add_f32_e32 v78, v78, v202
	v_add_f32_e32 v79, v79, v203
	global_store_dwordx4 v182, v[76:79], s[24:25]
	v_add_u32_e32 v183, 0x80000, v182
	global_load_dwordx4 v[200:203], v183, s[20:21]
	v_add_u32_e32 v182, 0x1000, v182
	s_waitcnt vmcnt(19)
	v_add_f32_e32 v80, v80, v204
	v_add_f32_e32 v81, v81, v205
	v_add_f32_e32 v82, v82, v206
	v_add_f32_e32 v83, v83, v207
	global_store_dwordx4 v182, v[80:83], s[24:25]
	v_add_u32_e32 v183, 0x80000, v182
	global_load_dwordx4 v[204:207], v183, s[20:21]
	v_add_u32_e32 v182, 0x1000, v182
	s_waitcnt vmcnt(20)
	v_add_f32_e32 v84, v84, v208
	v_add_f32_e32 v85, v85, v209
	v_add_f32_e32 v86, v86, v210
	v_add_f32_e32 v87, v87, v211
	global_store_dwordx4 v182, v[84:87], s[24:25]
	v_add_u32_e32 v183, 0x80000, v182
	global_load_dwordx4 v[208:211], v183, s[20:21]
	v_add_u32_e32 v182, 0x1000, v182
	s_waitcnt vmcnt(21)
	v_add_f32_e32 v88, v88, v212
	v_add_f32_e32 v89, v89, v213
	v_add_f32_e32 v90, v90, v214
	v_add_f32_e32 v91, v91, v215
	global_store_dwordx4 v182, v[88:91], s[24:25]
	v_add_u32_e32 v183, 0x80000, v182
	global_load_dwordx4 v[212:215], v183, s[20:21]
	v_add_u32_e32 v182, 0x1000, v182
	s_waitcnt vmcnt(22)
	v_add_f32_e32 v92, v92, v216
	v_add_f32_e32 v93, v93, v217
	v_add_f32_e32 v94, v94, v218
	v_add_f32_e32 v95, v95, v219
	global_store_dwordx4 v182, v[92:95], s[24:25]
	v_add_u32_e32 v183, 0x80000, v182
	global_load_dwordx4 v[216:219], v183, s[20:21]
	v_add_u32_e32 v182, 0x1000, v182
	s_waitcnt vmcnt(23)
	v_add_f32_e32 v96, v96, v220
	v_add_f32_e32 v97, v97, v221
	v_add_f32_e32 v98, v98, v222
	v_add_f32_e32 v99, v99, v223
	global_store_dwordx4 v182, v[96:99], s[24:25]
	v_add_u32_e32 v183, 0x80000, v182
	global_load_dwordx4 v[220:223], v183, s[20:21]
	v_add_u32_e32 v182, 0x1000, v182
	s_waitcnt vmcnt(24)
	v_add_f32_e32 v100, v100, v224
	v_add_f32_e32 v101, v101, v225
	v_add_f32_e32 v102, v102, v226
	v_add_f32_e32 v103, v103, v227
	global_store_dwordx4 v182, v[100:103], s[24:25]
	v_add_u32_e32 v183, 0x80000, v182
	global_load_dwordx4 v[224:227], v183, s[20:21]
	v_add_u32_e32 v182, 0x1000, v182
	s_waitcnt vmcnt(25)
	v_add_f32_e32 v104, v104, v228
	v_add_f32_e32 v105, v105, v229
	v_add_f32_e32 v106, v106, v230
	v_add_f32_e32 v107, v107, v231
	global_store_dwordx4 v182, v[104:107], s[24:25]
	v_add_u32_e32 v183, 0x80000, v182
	global_load_dwordx4 v[228:231], v183, s[20:21]
	v_add_u32_e32 v182, 0x1000, v182
	s_waitcnt vmcnt(26)
	v_add_f32_e32 v108, v108, v232
	v_add_f32_e32 v109, v109, v233
	v_add_f32_e32 v110, v110, v234
	v_add_f32_e32 v111, v111, v235
	global_store_dwordx4 v182, v[108:111], s[24:25]
	v_add_u32_e32 v183, 0x80000, v182
	global_load_dwordx4 v[232:235], v183, s[20:21]
	v_add_u32_e32 v182, 0x1000, v182
	s_waitcnt vmcnt(27)
	v_add_f32_e32 v112, v112, v236
	v_add_f32_e32 v113, v113, v237
	v_add_f32_e32 v114, v114, v238
	v_add_f32_e32 v115, v115, v239
	global_store_dwordx4 v182, v[112:115], s[24:25]
	v_add_u32_e32 v183, 0x80000, v182
	global_load_dwordx4 v[236:239], v183, s[20:21]
	v_add_u32_e32 v182, 0x1000, v182
	s_waitcnt vmcnt(28)
	v_add_f32_e32 v116, v116, v240
	v_add_f32_e32 v117, v117, v241
	v_add_f32_e32 v118, v118, v242
	v_add_f32_e32 v119, v119, v243
	global_store_dwordx4 v182, v[116:119], s[24:25]
	v_add_u32_e32 v183, 0x80000, v182
	global_load_dwordx4 v[240:243], v183, s[20:21]
	v_add_u32_e32 v182, 0x1000, v182
	s_waitcnt vmcnt(29)
	v_add_f32_e32 v120, v120, v244
	v_add_f32_e32 v121, v121, v245
	v_add_f32_e32 v122, v122, v246
	v_add_f32_e32 v123, v123, v247
	global_store_dwordx4 v182, v[120:123], s[24:25]
	v_add_u32_e32 v183, 0x80000, v182
	global_load_dwordx4 v[244:247], v183, s[20:21]
	v_add_u32_e32 v182, 0x1000, v182
	s_waitcnt vmcnt(30)
	v_add_f32_e32 v124, v124, v248
	v_add_f32_e32 v125, v125, v249
	v_add_f32_e32 v126, v126, v250
	v_add_f32_e32 v127, v127, v251
	global_store_dwordx4 v182, v[124:127], s[24:25]
	v_add_u32_e32 v183, 0x80000, v182
	global_load_dwordx4 v[248:251], v183, s[20:21]
	v_add_u32_e32 v181, 0x80000, v181
	ds_write_b128 v178, v[56:59]
	ds_write_b128 v178, v[60:63] offset:64
	ds_write_b128 v178, v[40:43] offset:16640
	ds_write_b128 v178, v[44:47] offset:16704
	ds_write_b128 v178, v[24:27] offset:33280
	ds_write_b128 v178, v[28:31] offset:33344
	ds_write_b128 v178, v[8:11] offset:49920
	ds_write_b128 v178, v[12:15] offset:49984
	ds_write_b128 v178, v[48:51] offset:512
	ds_write_b128 v178, v[52:55] offset:576
	ds_write_b128 v178, v[32:35] offset:17152
	ds_write_b128 v178, v[36:39] offset:17216
	ds_write_b128 v178, v[16:19] offset:33792
	ds_write_b128 v178, v[20:23] offset:33856
	ds_write_b128 v178, v[0:3] offset:50432
	ds_write_b128 v178, v[4:7] offset:50496
	s_waitcnt lgkmcnt(0)
	s_barrier
;     ...
;         for (int r = 0; r < 4; ++r) {
;           const int row = m0 + wm * 64 + mf * 16 + 4 * g + r;
; #pragma unroll
;           for (int nf = 0; nf < 4; ++nf) {
;             const int col = n0 + wn * 64 + nf * 16 + l15;
;             rvv[r][nf] = resid ? resid[(size_t)row * 1024 + col] : xrow(p, row)[col];
;           }
;         }
;       }
; #pragma unroll
;       for (int r = 0; r < 4; ++r) {
;         const int row = m0 + wm * 64 + mf * 16 + 4 * g + r;
;         if (EPI == 0) {
;           u16* proj = (u16*)(p.ws + OFF_PROJ) + (size_t)row * PROJ_LD;
;           if (n0 < 2048) {
;             const float2* rope = (const float2*)(p.ws + OFF_ROPE);
;             const int pi = row < NPROMPT ? (row & 2047) : 2048 + ((row - NPROMPT) & 7);
; #pragma unroll
;             for (int np = 0; np < 2; ++np) {
;               const int pc = n0 + wn * 64 + np * 32;
;               const int i = ((pc & 255) >> 5) * 16 + l15;
;               const float2 cs = rope[pi * 128 + i];
;               const float x1 = acc[mf][2 * np][r], x2 = acc[mf][2 * np + 1][r];
;               float y1 = x1 * cs.x - x2 * cs.y, y2 = x1 * cs.y + x2 * cs.x;
;               if (pc >= 1024) { y1 *= 0.0625f; y2 *= 0.0625f; }
;               const int f1 = (pc & ~255) + i;
;               proj[f1] = f2bf(y1);
;               proj[f1 + 128] = f2bf(y2);
;             }
;           } else {
; #pragma unroll
;             for (int nf = 0; nf < 4; ++nf) proj[n0 + wn * 64 + nf * 16 + l15] = f2bf(acc[mf][nf][r]);
;           }
;         } else if (EPI == 1) {
; #pragma unroll
;           for (int nf = 0; nf < 4; ++nf) {
;             const int col = n0 + wn * 64 + nf * 16 + l15;
;             const float a = (NH > 0) ? accT[mf][nf][r] : acc[mf][nf][r];
;             outf[(size_t)row * 1024 + col] = rvv[r][nf] + a;
	ds_read_b128 v[64:67], v180
	ds_read_b128 v[68:71], v180 offset:1040
	ds_read_b128 v[72:75], v180 offset:2080
	ds_read_b128 v[76:79], v180 offset:3120
	ds_read_b128 v[80:83], v180 offset:4160
	ds_read_b128 v[84:87], v180 offset:5200
	ds_read_b128 v[88:91], v180 offset:6240
	ds_read_b128 v[92:95], v180 offset:7280
	ds_read_b128 v[96:99], v180 offset:8320
	ds_read_b128 v[100:103], v180 offset:9360
	ds_read_b128 v[104:107], v180 offset:10400
	ds_read_b128 v[108:111], v180 offset:11440
	ds_read_b128 v[112:115], v180 offset:12480
	ds_read_b128 v[116:119], v180 offset:13520
	ds_read_b128 v[120:123], v180 offset:14560
	ds_read_b128 v[124:127], v180 offset:15600
	s_waitcnt lgkmcnt(0)
	s_barrier
	v_mov_b32_e32 v182, v181
	s_waitcnt vmcnt(30)
	v_add_f32_e32 v64, v64, v184
	v_add_f32_e32 v65, v65, v185
	v_add_f32_e32 v66, v66, v186
	v_add_f32_e32 v67, v67, v187
	global_store_dwordx4 v182, v[64:67], s[24:25]
	v_add_u32_e32 v182, 0x1000, v182
	s_waitcnt vmcnt(29)
	v_add_f32_e32 v68, v68, v188
	v_add_f32_e32 v69, v69, v189
	v_add_f32_e32 v70, v70, v190
	v_add_f32_e32 v71, v71, v191
	global_store_dwordx4 v182, v[68:71], s[24:25]
	v_add_u32_e32 v182, 0x1000, v182
	s_waitcnt vmcnt(28)
	v_add_f32_e32 v72, v72, v196
	v_add_f32_e32 v73, v73, v197
	v_add_f32_e32 v74, v74, v198
	v_add_f32_e32 v75, v75, v199
	global_store_dwordx4 v182, v[72:75], s[24:25]
	v_add_u32_e32 v182, 0x1000, v182
	s_waitcnt vmcnt(27)
	v_add_f32_e32 v76, v76, v200
	v_add_f32_e32 v77, v77, v201
	v_add_f32_e32 v78, v78, v202
	v_add_f32_e32 v79, v79, v203
	global_store_dwordx4 v182, v[76:79], s[24:25]
	v_add_u32_e32 v182, 0x1000, v182
	s_waitcnt vmcnt(26)
	v_add_f32_e32 v80, v80, v204
	v_add_f32_e32 v81, v81, v205
	v_add_f32_e32 v82, v82, v206
	v_add_f32_e32 v83, v83, v207
	global_store_dwordx4 v182, v[80:83], s[24:25]
	v_add_u32_e32 v182, 0x1000, v182
	s_waitcnt vmcnt(25)
	v_add_f32_e32 v84, v84, v208
	v_add_f32_e32 v85, v85, v209
	v_add_f32_e32 v86, v86, v210
	v_add_f32_e32 v87, v87, v211
	global_store_dwordx4 v182, v[84:87], s[24:25]
	v_add_u32_e32 v182, 0x1000, v182
	s_waitcnt vmcnt(24)
	v_add_f32_e32 v88, v88, v212
	v_add_f32_e32 v89, v89, v213
	v_add_f32_e32 v90, v90, v214
	v_add_f32_e32 v91, v91, v215
	global_store_dwordx4 v182, v[88:91], s[24:25]
	v_add_u32_e32 v182, 0x1000, v182
	s_waitcnt vmcnt(23)
	v_add_f32_e32 v92, v92, v216
	v_add_f32_e32 v93, v93, v217
	v_add_f32_e32 v94, v94, v218
	v_add_f32_e32 v95, v95, v219
	global_store_dwordx4 v182, v[92:95], s[24:25]
	v_add_u32_e32 v182, 0x1000, v182
	s_waitcnt vmcnt(22)
	v_add_f32_e32 v96, v96, v220
	v_add_f32_e32 v97, v97, v221
	v_add_f32_e32 v98, v98, v222
	v_add_f32_e32 v99, v99, v223
	global_store_dwordx4 v182, v[96:99], s[24:25]
	v_add_u32_e32 v182, 0x1000, v182
	s_waitcnt vmcnt(21)
	v_add_f32_e32 v100, v100, v224
	v_add_f32_e32 v101, v101, v225
	v_add_f32_e32 v102, v102, v226
	v_add_f32_e32 v103, v103, v227
	global_store_dwordx4 v182, v[100:103], s[24:25]
	v_add_u32_e32 v182, 0x1000, v182
	s_waitcnt vmcnt(20)
	v_add_f32_e32 v104, v104, v228
	v_add_f32_e32 v105, v105, v229
	v_add_f32_e32 v106, v106, v230
	v_add_f32_e32 v107, v107, v231
	global_store_dwordx4 v182, v[104:107], s[24:25]
	v_add_u32_e32 v182, 0x1000, v182
	s_waitcnt vmcnt(19)
	v_add_f32_e32 v108, v108, v232
	v_add_f32_e32 v109, v109, v233
	v_add_f32_e32 v110, v110, v234
	v_add_f32_e32 v111, v111, v235
	global_store_dwordx4 v182, v[108:111], s[24:25]
	v_add_u32_e32 v182, 0x1000, v182
	s_waitcnt vmcnt(18)
	v_add_f32_e32 v112, v112, v236
	v_add_f32_e32 v113, v113, v237
	v_add_f32_e32 v114, v114, v238
	v_add_f32_e32 v115, v115, v239
	global_store_dwordx4 v182, v[112:115], s[24:25]
	v_add_u32_e32 v182, 0x1000, v182
	s_waitcnt vmcnt(17)
	v_add_f32_e32 v116, v116, v240
	v_add_f32_e32 v117, v117, v241
	v_add_f32_e32 v118, v118, v242
	v_add_f32_e32 v119, v119, v243
	global_store_dwordx4 v182, v[116:119], s[24:25]
	v_add_u32_e32 v182, 0x1000, v182
	s_waitcnt vmcnt(16)
	v_add_f32_e32 v120, v120, v244
	v_add_f32_e32 v121, v121, v245
	v_add_f32_e32 v122, v122, v246
	v_add_f32_e32 v123, v123, v247
	global_store_dwordx4 v182, v[120:123], s[24:25]
	v_add_u32_e32 v182, 0x1000, v182
	s_waitcnt vmcnt(15)
	v_add_f32_e32 v124, v124, v248
	v_add_f32_e32 v125, v125, v249
	v_add_f32_e32 v126, v126, v250
	v_add_f32_e32 v127, v127, v251
	global_store_dwordx4 v182, v[124:127], s[24:25]
	s_waitcnt vmcnt(0)
	s_barrier
	s_add_i32 s70, s70, s96
	s_cmp_lt_u32 s70, 0x100
	s_cbranch_scc1 .Lq8_tile
